# top-k find_bin: uniform-lane ds_bpermute broadcasts replaced by v_readlane (on top of v13)
# baseline (speedup 1.0000x reference)
; __device__ __forceinline__ int find_bin(const unsigned* hist, int& need, int lane, int& binc) {
;     const int base = 1023 - 16 * lane; unsigned s = 0;
; #pragma unroll
;     for (int i = 0; i < 16; ++i) { const unsigned w = hist[base - ((i + lane) & 15)]; s += (w & 0xffffu) + (w >> 16); }
;     const unsigned p = wave_incl_scan_dpp(s);
;     const unsigned long long bal = __ballot(p >= (unsigned)need);
;     const int L = bal ? (__ffsll((long long)bal) - 1) : 63;
;     const unsigned excl = __shfl(p - s, L);
;     const int b0 = 1023 - 16 * L, t = lane & 31;
;     const unsigned w2 = hist[b0 - (t >> 1)];
;     const unsigned v2 = (lane < 32) ? ((t & 1) ? (w2 & 0xffffu) : (w2 >> 16)) : 0u;
.LBB0_913:
	s_lshl_b32 s0, s61, 12
	v_lshlrev_b32_e32 v129, 4, v222
	v_add_u32_e32 v11, 1, v124
	s_waitcnt vmcnt(3)
	v_add_u32_e32 v108, 2, v124
	v_add_u32_e32 v109, 3, v124
	v_add_u32_e32 v110, 4, v124
	v_add_u32_e32 v111, 5, v124
	s_waitcnt vmcnt(1)
	v_add_u32_e32 v118, 6, v124
	v_add_u32_e32 v119, 7, v124
	s_add_i32 s23, s0, 0
	v_xor_b32_e32 v8, 0x3f0, v129
	v_and_b32_e32 v11, 15, v11
	v_and_b32_e32 v108, 15, v108
	v_and_b32_e32 v109, 15, v109
	v_and_b32_e32 v110, 15, v110
	v_and_b32_e32 v111, 15, v111
	v_and_b32_e32 v118, 15, v118
	v_and_b32_e32 v119, 15, v119
	s_add_i32 s23, s23, 0x20080
	v_sub_u32_e32 v112, v8, v125
	v_sub_u32_e32 v113, v8, v11
	v_sub_u32_e32 v114, v8, v108
	v_sub_u32_e32 v115, v8, v109
	v_sub_u32_e32 v116, v8, v110
	v_sub_u32_e32 v117, v8, v111
	v_sub_u32_e32 v118, v8, v118
	v_sub_u32_e32 v119, v8, v119
	v_lshl_add_u32 v10, v112, 2, s23
	v_lshl_add_u32 v11, v113, 2, s23
	v_lshl_add_u32 v108, v114, 2, s23
	v_lshl_add_u32 v109, v115, 2, s23
	v_lshl_add_u32 v110, v116, 2, s23
	v_lshl_add_u32 v111, v117, 2, s23
	s_waitcnt vmcnt(0)
	v_lshl_add_u32 v120, v118, 2, s23
	v_lshl_add_u32 v121, v119, 2, s23
	ds_read_b32 v10, v10 offset:60
	ds_read_b32 v11, v11 offset:60
	ds_read_b32 v108, v108 offset:60
	ds_read_b32 v109, v109 offset:60
	ds_read_b32 v110, v110 offset:60
	ds_read_b32 v111, v111 offset:60
	ds_read_b32 v120, v120 offset:60
	ds_read_b32 v121, v121 offset:60
	s_waitcnt lgkmcnt(7)
	v_add_u32_sdwa v10, v10, v10 dst_sel:DWORD dst_unused:UNUSED_PAD src0_sel:WORD_1 src1_sel:WORD_0
	s_waitcnt lgkmcnt(6)
	v_and_b32_e32 v122, 0xffff, v11
	v_lshrrev_b32_e32 v11, 16, v11
	v_add3_u32 v10, v10, v11, v122
	s_waitcnt lgkmcnt(5)
	v_and_b32_e32 v11, 0xffff, v108
	v_lshrrev_b32_e32 v108, 16, v108
	v_add3_u32 v10, v10, v108, v11
	s_waitcnt lgkmcnt(4)
	v_and_b32_e32 v11, 0xffff, v109
	v_lshrrev_b32_e32 v108, 16, v109
	v_add3_u32 v10, v10, v108, v11
	s_waitcnt lgkmcnt(3)
	v_and_b32_e32 v11, 0xffff, v110
	v_lshrrev_b32_e32 v108, 16, v110
	v_add3_u32 v10, v10, v108, v11
	s_waitcnt lgkmcnt(2)
	v_and_b32_e32 v11, 0xffff, v111
	v_lshrrev_b32_e32 v108, 16, v111
	v_add3_u32 v10, v10, v108, v11
	s_waitcnt lgkmcnt(1)
	v_and_b32_e32 v11, 0xffff, v120
	v_lshrrev_b32_e32 v108, 16, v120
	v_add3_u32 v10, v10, v108, v11
	s_waitcnt lgkmcnt(0)
	v_and_b32_e32 v11, 0xffff, v121
	v_lshrrev_b32_e32 v108, 16, v121
	v_add3_u32 v10, v10, v108, v11
	v_add_u32_e32 v108, 9, v124
	v_add_u32_e32 v109, 10, v124
	v_add_u32_e32 v110, 11, v124
	v_add_u32_e32 v111, 12, v124
	v_add_u32_e32 v120, 13, v124
	v_add_u32_e32 v128, 14, v124
	v_add_u32_e32 v130, -1, v124
	v_xor_b32_e32 v11, 8, v125
	v_and_b32_e32 v108, 15, v108
	v_and_b32_e32 v109, 15, v109
	v_and_b32_e32 v110, 15, v110
	v_and_b32_e32 v111, 15, v111
	v_and_b32_e32 v120, 15, v120
	v_and_b32_e32 v128, 15, v128
	v_and_b32_e32 v130, 15, v130
	v_sub_u32_e32 v121, v8, v11
	v_sub_u32_e32 v122, v8, v108
	v_sub_u32_e32 v123, v8, v109
	v_sub_u32_e32 v125, v8, v110
	v_sub_u32_e32 v126, v8, v111
	v_sub_u32_e32 v127, v8, v120
	v_sub_u32_e32 v128, v8, v128
	v_sub_u32_e32 v130, v8, v130
	v_lshl_add_u32 v11, v121, 2, s23
	v_lshl_add_u32 v108, v122, 2, s23
	v_lshl_add_u32 v109, v123, 2, s23
	v_lshl_add_u32 v110, v125, 2, s23
	v_lshl_add_u32 v111, v126, 2, s23
	v_lshl_add_u32 v120, v127, 2, s23
	v_lshl_add_u32 v131, v128, 2, s23
	v_lshl_add_u32 v8, v130, 2, s23
	ds_read_b32 v11, v11 offset:60
	ds_read_b32 v108, v108 offset:60
	ds_read_b32 v109, v109 offset:60
	ds_read_b32 v110, v110 offset:60
	ds_read_b32 v111, v111 offset:60
	ds_read_b32 v120, v120 offset:60
	ds_read_b32 v131, v131 offset:60
	ds_read_b32 v8, v8 offset:60
	s_waitcnt lgkmcnt(7)
	v_and_b32_e32 v132, 0xffff, v11
	v_lshrrev_b32_e32 v11, 16, v11
	v_add3_u32 v10, v10, v11, v132
	s_waitcnt lgkmcnt(6)
	v_and_b32_e32 v11, 0xffff, v108
	v_lshrrev_b32_e32 v108, 16, v108
	v_add3_u32 v10, v10, v108, v11
	s_waitcnt lgkmcnt(5)
	v_and_b32_e32 v11, 0xffff, v109
	v_lshrrev_b32_e32 v108, 16, v109
	v_add3_u32 v10, v10, v108, v11
	s_waitcnt lgkmcnt(4)
	v_and_b32_e32 v11, 0xffff, v110
	v_lshrrev_b32_e32 v108, 16, v110
	v_add3_u32 v10, v10, v108, v11
	s_waitcnt lgkmcnt(3)
	v_and_b32_e32 v11, 0xffff, v111
	v_lshrrev_b32_e32 v108, 16, v111
	v_add3_u32 v10, v10, v108, v11
	s_waitcnt lgkmcnt(2)
	v_and_b32_e32 v11, 0xffff, v120
	v_lshrrev_b32_e32 v108, 16, v120
	v_add3_u32 v10, v10, v108, v11
	s_waitcnt lgkmcnt(1)
	v_and_b32_e32 v11, 0xffff, v131
	v_lshrrev_b32_e32 v108, 16, v131
	v_add3_u32 v10, v10, v108, v11
	s_waitcnt lgkmcnt(0)
	v_and_b32_e32 v11, 0xffff, v8
	v_lshrrev_b32_e32 v8, 16, v8
	v_add3_u32 v8, v10, v8, v11
	v_cmp_gt_u32_e64 s[4:5], 32, v222
	s_nop 0
	v_add_u32_dpp v10, v8, v8 row_shr:1 row_mask:0xf bank_mask:0xf bound_ctrl:1
	s_nop 1
	v_add_u32_dpp v10, v10, v10 row_shr:2 row_mask:0xf bank_mask:0xf bound_ctrl:1
	s_nop 1
	v_add_u32_dpp v10, v10, v10 row_shr:4 row_mask:0xf bank_mask:0xf bound_ctrl:1
	s_nop 1
	v_add_u32_dpp v10, v10, v10 row_shr:8 row_mask:0xf bank_mask:0xf bound_ctrl:1
	s_nop 1
	v_add_u32_dpp v10, v10, v10 row_bcast:15 row_mask:0xa bank_mask:0xf
	s_nop 1
	v_add_u32_dpp v10, v10, v10 row_bcast:31 row_mask:0xc bank_mask:0xf
	v_cmp_lt_u32_e32 vcc, s39, v10
	s_ff1_i32_b64 s0, vcc
	s_cmp_lg_u64 vcc, 0
	s_cselect_b32 s0, s0, 63
	v_sub_u32_e32 v8, v10, v8
	v_or_b32_e32 v10, s0, v219
	v_lshlrev_b32_e32 v10, 2, v10
	v_readlane_b32 s98, v8, s0
	s_nop 1
	v_mov_b32_e32 v8, s98
	v_mov_b32_e32 v10, 0
	s_lshl_b32 s6, s0, 4
	s_and_saveexec_b64 s[0:1], s[4:5]
	s_cbranch_execz .LBB0_915
	v_lshrrev_b32_e32 v10, 1, v222
	s_xor_b32 s7, s6, 0x3f0
	v_sub_u32_e32 v10, s7, v10
	v_lshl_add_u32 v10, v10, 2, s23
	ds_read_b32 v10, v10 offset:60
	v_and_b32_e32 v11, 1, v124
	v_cmp_eq_u32_e32 vcc, 0, v11
	s_waitcnt lgkmcnt(0)
	s_nop 0
	v_cndmask_b32_sdwa v10, v10, v10, vcc dst_sel:DWORD dst_unused:UNUSED_PAD src0_sel:WORD_0 src1_sel:WORD_1
; __device__ __forceinline__ int find_bin(const unsigned* hist, int& need, int lane, int& binc) {
;     ...
;     const int b0 = 1023 - 16 * L, t = lane & 31;
;     const unsigned w2 = hist[b0 - (t >> 1)];
;     const unsigned v2 = (lane < 32) ? ((t & 1) ? (w2 & 0xffffu) : (w2 >> 16)) : 0u;
;     const unsigned p2 = wave_incl_scan_dpp(v2);
;     const unsigned long long bal2 = __ballot((lane < 32) && ((unsigned)excl + p2 >= (unsigned)need));
;     const int ts = bal2 ? (__ffsll((long long)bal2) - 1) : 31;
;     const int vs = (int)__shfl(v2, ts), ps = (int)__shfl(p2, ts);
;     int bin = 2 * (b0 - (ts >> 1)) + ((ts & 1) ? 0 : 1);
;     int fneed = need - ((int)excl + ps - vs), bc = vs;
;     if (fneed < 1) fneed = 1;
;     need = fneed; binc = bc; return bin;
; template <bool DUMMY> __device__ __forceinline__ void phase_dsa(const Args& a, unsigned char* lds) {
;     ...
;                     const int c1 = binc, nsure = 256 - need; const bool store_c = c1 <= CAP;
;                     if (hf == 0 && lane == 0) { CNT[12 + q] = (int)b1; CNT[16 + q] = need; CNT[8 + q] = c1; }
.LBB0_915:
	s_or_b64 exec, exec, s[0:1]
	s_nop 0
	v_add_u32_dpp v11, v10, v10 row_shr:1 row_mask:0xf bank_mask:0xf bound_ctrl:1
	s_bfe_u32 s8, s62, 0x10006
	s_xor_b32 s6, s6, 0x3ff
	v_add_u32_dpp v11, v11, v11 row_shr:2 row_mask:0xf bank_mask:0xf bound_ctrl:1
	s_nop 1
	v_add_u32_dpp v11, v11, v11 row_shr:4 row_mask:0xf bank_mask:0xf bound_ctrl:1
	s_nop 1
	v_add_u32_dpp v11, v11, v11 row_shr:8 row_mask:0xf bank_mask:0xf bound_ctrl:1
	s_nop 1
	v_add_u32_dpp v11, v11, v11 row_bcast:15 row_mask:0xa bank_mask:0xf
	s_nop 1
	v_add_u32_dpp v11, v11, v11 row_bcast:31 row_mask:0xc bank_mask:0xf
	s_waitcnt lgkmcnt(0)
	v_add_u32_e32 v108, v11, v8
	v_cmp_lt_u32_e32 vcc, s39, v108
	s_and_b64 s[0:1], s[4:5], vcc
	v_cndmask_b32_e64 v108, 0, 1, s[0:1]
	v_cmp_ne_u32_e32 vcc, 0, v108
	s_ff1_i32_b64 s0, vcc
	s_cmp_lg_u64 vcc, 0
	s_cselect_b32 s0, s0, 31
	v_or_b32_e32 v108, s0, v219
	v_lshlrev_b32_e32 v108, 2, v108
	v_readlane_b32 s98, v10, s0
	v_readlane_b32 s99, v11, s0
	s_lshr_b32 s1, s0, 1
	s_sub_i32 s1, s6, s1
	s_lshl_b32 s1, s1, 1
	s_and_b32 s0, s0, 1
	s_waitcnt lgkmcnt(0)
	v_mov_b32_e32 v131, s98
	v_mov_b32_e32 v10, s99
	v_add_u32_e32 v8, v8, v10
	v_sub_u32_e32 v8, v131, v8
	v_add_u32_e32 v8, 0x100, v8
	s_or_b32 s0, s1, s0
	v_max_i32_e32 v132, 1, v8
	v_or_b32_e32 v8, s8, v222
	s_xor_b32 s24, s0, 1
	v_cmp_eq_u32_e32 vcc, 0, v8
	s_and_saveexec_b64 s[0:1], vcc
	s_cbranch_execz .LBB0_917
	s_lshl_b32 s6, s61, 2
	s_add_i32 s6, s6, 0
	s_add_i32 s6, s6, 0x26080
	v_mov_b32_e32 v8, s6
	v_mov_b32_e32 v10, s24
	ds_write_b32 v8, v132 offset:64
	ds_write2_b32 v8, v131, v10 offset0:8 offset1:12

; __device__ __forceinline__ void lds_order() { asm volatile("" ::: "memory"); }
; __device__ __forceinline__ int find_bin128(const unsigned* sh, int& need, int lane, int& binc) {
;     const unsigned hi = sh[127 - 2 * lane], lo = sh[126 - 2 * lane]; const unsigned s = hi + lo;
;     const unsigned p = wave_incl_scan_dpp(s);
;     const unsigned long long bal = __ballot(p >= (unsigned)need);
;     const int L = bal ? (__ffsll((long long)bal) - 1) : 63;
;     const int excl = (int)__shfl(p - s, L); const int hiL = (int)__shfl(hi, L), loL = (int)__shfl(lo, L);
;     int bin, fneed, bc;
;     if (excl + hiL >= need) { bin = 127 - 2 * L; fneed = need - excl; bc = hiL; } else { bin = 126 - 2 * L; fneed = need - excl - hiL; bc = loL; }
;     if (fneed < 1) fneed = 1;
;     need = fneed; binc = bc; return bin;
; }
; template <bool DUMMY> __device__ __forceinline__ void phase_dsa(const Args& a, unsigned char* lds) {
;     ...
;                         sh[2 * lane] = 0u; sh[2 * lane + 1] = 0u; lds_order();
; #pragma unroll
;                         for (int t = 0; t < 7; ++t) if (ci[t] >= 0) atomicAdd(&sh[(ck[t] >> 14) & 127u], 1u);
;                         lds_order();
;                         const unsigned bA = (unsigned)find_bin128(sh, need, lane, binc);
;                         lds_order();
;                         sh[2 * lane] = 0u; sh[2 * lane + 1] = 0u; lds_order();
; #pragma unroll
;                         for (int t = 0; t < 7; ++t) if (ci[t] >= 0 && ((ck[t] >> 14) & 127u) == bA) atomicAdd(&sh[(ck[t] >> 7) & 127u], 1u);
.LBB0_981:
	s_or_b64 exec, exec, s[0:1]
	v_lshlrev_b32_e32 v123, 1, v222
	v_xor_b32_e32 v122, 0x7e, v123
	v_lshl_add_u32 v122, v122, 2, s78
	v_lshlrev_b32_e32 v123, 2, v123
	v_sub_u32_e32 v123, s78, v123
	ds_read_b32 v124, v122 offset:3588
	ds_read_b32 v125, v123 offset:4088
	ds_write_b64 v121, v[250:251] offset:3584
	s_waitcnt lgkmcnt(1)
	v_add_u32_e32 v125, v125, v124
	s_nop 1
	v_add_u32_dpp v126, v125, v125 row_shr:1 row_mask:0xf bank_mask:0xf bound_ctrl:1
	s_nop 1
	v_add_u32_dpp v126, v126, v126 row_shr:2 row_mask:0xf bank_mask:0xf bound_ctrl:1
	s_nop 1
	v_add_u32_dpp v126, v126, v126 row_shr:4 row_mask:0xf bank_mask:0xf bound_ctrl:1
	s_nop 1
	v_add_u32_dpp v126, v126, v126 row_shr:8 row_mask:0xf bank_mask:0xf bound_ctrl:1
	s_nop 1
	v_add_u32_dpp v126, v126, v126 row_bcast:15 row_mask:0xa bank_mask:0xf
	s_nop 1
	v_add_u32_dpp v126, v126, v126 row_bcast:31 row_mask:0xc bank_mask:0xf
	v_cmp_le_u32_e64 s[0:1], s79, v126
	s_ff1_i32_b64 s6, s[0:1]
	s_cmp_lg_u64 s[0:1], 0
	s_cselect_b32 s0, s6, 63
	v_sub_u32_e32 v125, v126, v125
	v_or_b32_e32 v126, s0, v219
	v_lshlrev_b32_e32 v126, 2, v126
	v_readlane_b32 s98, v125, s0
	v_readlane_b32 s99, v124, s0
	s_lshl_b32 s0, s0, 1
	s_xor_b32 s1, s0, 0x7f
	s_sub_i32 s0, 0x7e, s0
	v_mov_b32_e32 v127, s0
	s_waitcnt lgkmcnt(0)
	v_mov_b32_e32 v125, s98
	v_mov_b32_e32 v124, s99
	v_add_u32_e32 v126, v124, v125
	v_mov_b32_e32 v124, s1
	v_cmp_gt_i32_e64 s[6:7], s79, v126
	s_nop 1
	v_cndmask_b32_e64 v124, v124, v127, s[6:7]
	s_and_saveexec_b64 s[22:23], s[16:17]
	s_cbranch_execz .LBB0_984
	v_bfe_u32 v127, v118, 14, 7
	v_cmp_eq_u32_e64 s[0:1], v127, v124
	s_and_b64 exec, exec, s[0:1]
	v_lshrrev_b32_e32 v127, 5, v118
	v_and_b32_e32 v127, 0x1fc, v127
	v_add_u32_e32 v127, s78, v127
	ds_add_u32 v127, v159 offset:3584

; __device__ __forceinline__ void lds_order() { asm volatile("" ::: "memory"); }
; __device__ __forceinline__ int find_bin128(const unsigned* sh, int& need, int lane, int& binc) {
;     const unsigned hi = sh[127 - 2 * lane], lo = sh[126 - 2 * lane]; const unsigned s = hi + lo;
;     const unsigned p = wave_incl_scan_dpp(s);
;     const unsigned long long bal = __ballot(p >= (unsigned)need);
;     const int L = bal ? (__ffsll((long long)bal) - 1) : 63;
;     const int excl = (int)__shfl(p - s, L); const int hiL = (int)__shfl(hi, L), loL = (int)__shfl(lo, L);
;     int bin, fneed, bc;
;     if (excl + hiL >= need) { bin = 127 - 2 * L; fneed = need - excl; bc = hiL; } else { bin = 126 - 2 * L; fneed = need - excl - hiL; bc = loL; }
;     if (fneed < 1) fneed = 1;
;     need = fneed; binc = bc; return bin;
; }
; template <bool DUMMY> __device__ __forceinline__ void phase_dsa(const Args& a, unsigned char* lds) {
;     ...
;                         lds_order();
;                         const unsigned bB = (unsigned)find_bin128(sh, need, lane, binc);
;                         const unsigned preB = (bA << 7) | bB;
;                         lds_order();
;                         sh[2 * lane] = 0u; sh[2 * lane + 1] = 0u; lds_order();
; #pragma unroll
;                         for (int t = 0; t < 7; ++t) if (ci[t] >= 0 && ((ck[t] >> 7) & 0x3fffu) == preB) atomicAdd(&sh[ck[t] & 127u], 1u);
.LBB0_1002:
	s_or_b64 exec, exec, s[22:23]
	ds_read_b32 v127, v122 offset:3588
	ds_read_b32 v128, v123 offset:4088
	v_cndmask_b32_e64 v125, v125, v126, s[6:7]
	v_sub_u32_e32 v125, s79, v125
	v_max_i32_e32 v125, 1, v125
	s_waitcnt lgkmcnt(0)
	v_add_u32_e32 v126, v128, v127
	ds_write_b64 v121, v[250:251] offset:3584
	s_nop 0
	v_add_u32_dpp v128, v126, v126 row_shr:1 row_mask:0xf bank_mask:0xf bound_ctrl:1
	s_nop 1
	v_add_u32_dpp v128, v128, v128 row_shr:2 row_mask:0xf bank_mask:0xf bound_ctrl:1
	s_nop 1
	v_add_u32_dpp v128, v128, v128 row_shr:4 row_mask:0xf bank_mask:0xf bound_ctrl:1
	s_nop 1
	v_add_u32_dpp v128, v128, v128 row_shr:8 row_mask:0xf bank_mask:0xf bound_ctrl:1
	s_nop 1
	v_add_u32_dpp v128, v128, v128 row_bcast:15 row_mask:0xa bank_mask:0xf
	s_nop 1
	v_add_u32_dpp v128, v128, v128 row_bcast:31 row_mask:0xc bank_mask:0xf
	v_cmp_ge_u32_e64 s[0:1], v128, v125
	s_ff1_i32_b64 s6, s[0:1]
	s_cmp_lg_u64 s[0:1], 0
	s_cselect_b32 s0, s6, 63
	v_sub_u32_e32 v126, v128, v126
	v_or_b32_e32 v128, s0, v219
	v_lshlrev_b32_e32 v128, 2, v128
	v_readlane_b32 s98, v126, s0
	v_readlane_b32 s99, v127, s0
	s_lshl_b32 s0, s0, 1
	s_xor_b32 s1, s0, 0x7f
	s_sub_i32 s0, 0x7e, s0
	v_mov_b32_e32 v128, s1
	s_waitcnt lgkmcnt(0)
	v_mov_b32_e32 v126, s98
	v_mov_b32_e32 v127, s99
	v_add_u32_e32 v127, v127, v126
	v_mov_b32_e32 v129, s0
	v_cmp_lt_i32_e64 s[6:7], v127, v125
	s_nop 1
	v_cndmask_b32_e64 v128, v128, v129, s[6:7]
	v_lshl_or_b32 v124, v124, 7, v128
	s_and_saveexec_b64 s[22:23], s[16:17]
	s_cbranch_execz .LBB0_1005
	v_bfe_u32 v121, v118, 7, 14
	v_cmp_eq_u32_e64 s[0:1], v121, v124
	s_and_b64 exec, exec, s[0:1]
	v_and_b32_e32 v121, 0x7f, v118
	v_lshl_add_u32 v121, v121, 2, s78
	ds_add_u32 v121, v159 offset:3584

; __device__ __forceinline__ void lds_order() { asm volatile("" ::: "memory"); }
; __device__ __forceinline__ int find_bin128(const unsigned* sh, int& need, int lane, int& binc) {
;     const unsigned hi = sh[127 - 2 * lane], lo = sh[126 - 2 * lane]; const unsigned s = hi + lo;
;     const unsigned p = wave_incl_scan_dpp(s);
;     const unsigned long long bal = __ballot(p >= (unsigned)need);
;     const int L = bal ? (__ffsll((long long)bal) - 1) : 63;
;     const int excl = (int)__shfl(p - s, L); const int hiL = (int)__shfl(hi, L), loL = (int)__shfl(lo, L);
;     int bin, fneed, bc;
;     if (excl + hiL >= need) { bin = 127 - 2 * L; fneed = need - excl; bc = hiL; } else { bin = 126 - 2 * L; fneed = need - excl - hiL; bc = loL; }
;     if (fneed < 1) fneed = 1;
;     need = fneed; binc = bc; return bin;
; }
; template <bool DUMMY> __device__ __forceinline__ void phase_dsa(const Args& a, unsigned char* lds) {
;     ...
;                         lds_order();
;                         const unsigned bC = (unsigned)find_bin128(sh, need, lane, binc);
;                         const unsigned T = (b1 << 21) | (preB << 7) | bC;
;                         const int tie_total = binc, need_t = need;
;                         int cnt = 0;
; #pragma unroll
;                         for (int t = 0; t < 7; ++t) {
;                             const bool valid = ci[t] >= 0;
;                             bool sel = valid && (ck[t] > T);
;                             if (valid && ck[t] == T) {
;                                 if (tie_total == need_t) sel = true;
;                                 else { int rank = 0; for (int j = 0; j < c; ++j) rank += (hist[2 * j] == T && (int)hist[2 * j + 1] < ci[t]) ? 1 : 0; sel = rank < need_t; }
.LBB0_1023:
	s_or_b64 exec, exec, s[22:23]
	ds_read_b32 v121, v122 offset:3588
	ds_read_b32 v122, v123 offset:4088
	v_cndmask_b32_e64 v123, v126, v127, s[6:7]
	v_sub_u32_e32 v123, v125, v123
	v_max_i32_e32 v123, 1, v123
	s_mov_b64 s[26:27], 0
	s_waitcnt lgkmcnt(0)
	v_add_u32_e32 v125, v122, v121
	s_nop 1
	v_add_u32_dpp v126, v125, v125 row_shr:1 row_mask:0xf bank_mask:0xf bound_ctrl:1
	s_nop 1
	v_add_u32_dpp v126, v126, v126 row_shr:2 row_mask:0xf bank_mask:0xf bound_ctrl:1
	s_nop 1
	v_add_u32_dpp v126, v126, v126 row_shr:4 row_mask:0xf bank_mask:0xf bound_ctrl:1
	s_nop 1
	v_add_u32_dpp v126, v126, v126 row_shr:8 row_mask:0xf bank_mask:0xf bound_ctrl:1
	s_nop 1
	v_add_u32_dpp v126, v126, v126 row_bcast:15 row_mask:0xa bank_mask:0xf
	s_nop 1
	v_add_u32_dpp v126, v126, v126 row_bcast:31 row_mask:0xc bank_mask:0xf
	v_cmp_ge_u32_e64 s[0:1], v126, v123
	s_ff1_i32_b64 s6, s[0:1]
	s_cmp_lg_u64 s[0:1], 0
	s_cselect_b32 s0, s6, 63
	v_sub_u32_e32 v125, v126, v125
	v_or_b32_e32 v126, s0, v219
	v_lshlrev_b32_e32 v126, 2, v126
	v_readlane_b32 s98, v125, s0
	v_readlane_b32 s99, v121, s0
	v_readlane_b32 s100, v122, s0
	s_lshl_b32 s0, s0, 1
	s_xor_b32 s1, s0, 0x7f
	s_sub_i32 s0, 0x7e, s0
	s_waitcnt lgkmcnt(1)
	v_mov_b32_e32 v125, s98
	v_mov_b32_e32 v121, s99
	v_mov_b32_e32 v122, s100
	v_add_u32_e32 v126, v121, v125
	v_mov_b32_e32 v127, s1
	v_mov_b32_e32 v128, s0
	v_cmp_lt_i32_e64 s[0:1], v126, v123
	s_nop 1
	v_cndmask_b32_e64 v125, v125, v126, s[0:1]
	v_cndmask_b32_e64 v127, v127, v128, s[0:1]
	s_waitcnt lgkmcnt(0)
	v_cndmask_b32_e64 v126, v121, v122, s[0:1]
	v_sub_u32_e32 v121, v123, v125
	s_lshl_b32 s0, s24, 21
	v_max_i32_e32 v121, 1, v121
	v_lshl_add_u32 v122, v124, 7, s0
	s_cmp_lt_i32 s77, 1
	v_or_b32_e32 v122, v127, v122
	v_cmp_eq_u32_e64 s[6:7], v126, v121
	s_cselect_b64 s[22:23], -1, 0
	s_and_saveexec_b64 s[24:25], s[16:17]
	s_cbranch_execz .LBB0_1110
	v_cmp_ne_u32_e64 s[0:1], v118, v122
	s_or_b64 s[16:17], s[0:1], s[6:7]
	v_cmp_ge_u32_e64 s[0:1], v118, v122
	s_nor_b64 s[28:29], s[22:23], s[16:17]
	s_xor_b64 s[16:17], s[16:17], -1
	s_or_b64 s[16:17], s[16:17], s[0:1]
	s_and_saveexec_b64 s[26:27], s[28:29]
	s_cbranch_execz .LBB0_1109
	s_add_i32 s0, s77, -1
	s_cmp_lt_u32 s0, 7
	s_cbranch_scc1 .LBB0_1102
	s_and_b32 s81, s77, 0x7ffffff8
	s_add_i32 s82, s80, 0x20080
	s_mov_b32 s83, 0
	v_mov_b32_e32 v123, 0
	s_branch .LBB0_1028
